# grid barrier: non-leader workgroups poll the cross-XCD generation word directly (one relay hop less)
# baseline (speedup 1.0000x reference)
; __device__ __forceinline__ unsigned xb_ld(unsigned* p)              { return __hip_atomic_load(p, __ATOMIC_RELAXED, __HIP_MEMORY_SCOPE_AGENT); }
; __device__ __forceinline__ unsigned xb_add(unsigned* p, unsigned v) { return __hip_atomic_fetch_add(p, v, __ATOMIC_RELAXED, __HIP_MEMORY_SCOPE_AGENT); }
; #define XB_SPIN(cond, bar) do { unsigned _sp = 0; while (cond) { __builtin_amdgcn_s_sleep(1); \
;     if ((++_sp & 255u) == 0u) { if (xb_ld(&(bar)[XB_TMO])) break; if (_sp > XB_SPIN_CAP) { atomicAdd(&(bar)[XB_TMO], 1u); break; } } } } while (0)
; __device__ __forceinline__ void xcd_barrier(const XcdBarrier& b) {
;     ...
;         const unsigned old = xb_add(&bar[XB_XSUB(b.x)], 1u);
;         const unsigned gen = old / nloc;
;         if (old + 1u == (gen + 1u) * nloc) {
;             __builtin_amdgcn_fence(__ATOMIC_RELEASE, "agent");
;             asm volatile("s_waitcnt vmcnt(0)" ::: "memory");
;             const unsigned og = xb_add(&bar[XB_TOP], 1u);
;             const unsigned tg = og / nx;
;             if (og + 1u == (tg + 1u) * nx) xb_add(&bar[XB_TOPGEN], 1u);
;             else XB_SPIN(xb_ld(&bar[XB_TOPGEN]) == tg, bar);
;             __builtin_amdgcn_fence(__ATOMIC_ACQUIRE, "agent");
;             xb_add(&bar[XB_XGEN(b.x)], 1u);
;             asm volatile("s_waitcnt vmcnt(0)" ::: "memory");
;         } else {
;             XB_SPIN(xb_ld(&bar[XB_XGEN(b.x)]) == gen, bar);
.LBB0_46:
	s_or_b64 exec, exec, s[12:13]
	v_cvt_f32_u32_e32 v4, v2
	s_waitcnt vmcnt(0)
	v_readfirstlane_b32 s0, v3
	v_sub_u32_e32 v3, 0, v2
	v_rcp_iflag_f32_e32 v4, v4
	v_add_u32_e32 v5, s0, v1
	v_mul_f32_e32 v4, 0x4f7ffffe, v4
	v_cvt_u32_f32_e32 v4, v4
	v_mul_lo_u32 v1, v3, v4
	v_mul_hi_u32 v1, v4, v1
	v_add_u32_e32 v1, v4, v1
	v_mul_hi_u32 v1, v5, v1
	v_mul_lo_u32 v3, v1, v2
	v_sub_u32_e32 v3, v5, v3
	v_add_u32_e32 v4, 1, v1
	v_cmp_ge_u32_e32 vcc, v3, v2
	s_nop 1
	v_cndmask_b32_e32 v1, v1, v4, vcc
	v_sub_u32_e32 v4, v3, v2
	v_cndmask_b32_e32 v3, v3, v4, vcc
	v_add_u32_e32 v4, 1, v1
	v_cmp_ge_u32_e32 vcc, v3, v2
	v_add_u32_e32 v3, 1, v5
	s_nop 0
	v_cndmask_b32_e32 v1, v1, v4, vcc
	v_mul_lo_u32 v4, v2, v1
	v_add_u32_e32 v2, v4, v2
	v_cmp_ne_u32_e32 vcc, v3, v2
	s_and_saveexec_b64 s[0:1], vcc
	s_xor_b64 s[10:11], exec, s[0:1]
	s_cbranch_execz .LBB0_60
	s_waitcnt lgkmcnt(0)
	v_mov_b32_e32 v0, 0x183500
	buffer_inv sc1
	global_load_dword v0, v0, s[6:7] sc1
	s_add_u32 s16, s6, 0x183500
	s_addc_u32 s17, s7, 0
	s_waitcnt vmcnt(0)
	v_cmp_eq_u32_e32 vcc, v0, v1
	s_and_saveexec_b64 s[12:13], vcc
	s_cbranch_execz .LBB0_59
	s_add_u32 s14, s6, 0x180200
	s_addc_u32 s15, s7, 0
	s_mov_b32 s0, 1
	s_mov_b64 s[18:19], 0
	v_mov_b32_e32 v0, 0
	s_branch .LBB0_50

; __device__ __forceinline__ unsigned xb_ld(unsigned* p)              { return __hip_atomic_load(p, __ATOMIC_RELAXED, __HIP_MEMORY_SCOPE_AGENT); }
; __device__ __forceinline__ unsigned xb_add(unsigned* p, unsigned v) { return __hip_atomic_fetch_add(p, v, __ATOMIC_RELAXED, __HIP_MEMORY_SCOPE_AGENT); }
; #define XB_SPIN(cond, bar) do { unsigned _sp = 0; while (cond) { __builtin_amdgcn_s_sleep(1); \
;     if ((++_sp & 255u) == 0u) { if (xb_ld(&(bar)[XB_TMO])) break; if (_sp > XB_SPIN_CAP) { atomicAdd(&(bar)[XB_TMO], 1u); break; } } } } while (0)
; __device__ __forceinline__ void xcd_barrier(const XcdBarrier& b) {
;     ...
;         const unsigned old = xb_add(&bar[XB_XSUB(b.x)], 1u);
;         const unsigned gen = old / nloc;
;         if (old + 1u == (gen + 1u) * nloc) {
;             __builtin_amdgcn_fence(__ATOMIC_RELEASE, "agent");
;             asm volatile("s_waitcnt vmcnt(0)" ::: "memory");
;             const unsigned og = xb_add(&bar[XB_TOP], 1u);
;             const unsigned tg = og / nx;
;             if (og + 1u == (tg + 1u) * nx) xb_add(&bar[XB_TOPGEN], 1u);
;             else XB_SPIN(xb_ld(&bar[XB_TOPGEN]) == tg, bar);
;             __builtin_amdgcn_fence(__ATOMIC_ACQUIRE, "agent");
;             xb_add(&bar[XB_XGEN(b.x)], 1u);
;             asm volatile("s_waitcnt vmcnt(0)" ::: "memory");
;         } else {
;             XB_SPIN(xb_ld(&bar[XB_XGEN(b.x)]) == gen, bar);
.LBB0_234:
	s_or_b64 exec, exec, s[14:15]
	v_cvt_f32_u32_e32 v5, v3
	s_waitcnt vmcnt(0)
	v_readfirstlane_b32 s0, v4
	v_sub_u32_e32 v4, 0, v3
	v_rcp_iflag_f32_e32 v5, v5
	v_add_u32_e32 v6, s0, v0
	v_mul_f32_e32 v5, 0x4f7ffffe, v5
	v_cvt_u32_f32_e32 v5, v5
	v_mul_lo_u32 v0, v4, v5
	v_mul_hi_u32 v0, v5, v0
	v_add_u32_e32 v0, v5, v0
	v_mul_hi_u32 v0, v6, v0
	v_mul_lo_u32 v4, v0, v3
	v_sub_u32_e32 v4, v6, v4
	v_add_u32_e32 v5, 1, v0
	v_cmp_ge_u32_e32 vcc, v4, v3
	s_nop 1
	v_cndmask_b32_e32 v0, v0, v5, vcc
	v_sub_u32_e32 v5, v4, v3
	v_cndmask_b32_e32 v4, v4, v5, vcc
	v_add_u32_e32 v5, 1, v0
	v_cmp_ge_u32_e32 vcc, v4, v3
	v_add_u32_e32 v4, 1, v6
	s_nop 0
	v_cndmask_b32_e32 v0, v0, v5, vcc
	v_mul_lo_u32 v5, v3, v0
	v_add_u32_e32 v3, v5, v3
	v_cmp_ne_u32_e32 vcc, v4, v3
	s_and_saveexec_b64 s[0:1], vcc
	s_xor_b64 s[12:13], exec, s[0:1]
	s_cbranch_execz .LBB0_248
	s_waitcnt lgkmcnt(0)
	v_mov_b32_e32 v2, 0x183500
	buffer_inv sc1
	global_load_dword v2, v2, s[8:9] sc1
	s_add_u32 s18, s8, 0x183500
	s_addc_u32 s19, s9, 0
	s_waitcnt vmcnt(0)
	v_cmp_eq_u32_e32 vcc, v2, v0
	s_and_saveexec_b64 s[14:15], vcc
	s_cbranch_execz .LBB0_247
	s_add_u32 s16, s8, 0x180200
	s_addc_u32 s17, s9, 0
	s_mov_b32 s0, 1
	s_mov_b64 s[20:21], 0
	s_branch .LBB0_238

; __device__ __forceinline__ unsigned xb_ld(unsigned* p)              { return __hip_atomic_load(p, __ATOMIC_RELAXED, __HIP_MEMORY_SCOPE_AGENT); }
; __device__ __forceinline__ unsigned xb_add(unsigned* p, unsigned v) { return __hip_atomic_fetch_add(p, v, __ATOMIC_RELAXED, __HIP_MEMORY_SCOPE_AGENT); }
; #define XB_SPIN(cond, bar) do { unsigned _sp = 0; while (cond) { __builtin_amdgcn_s_sleep(1); \
;     if ((++_sp & 255u) == 0u) { if (xb_ld(&(bar)[XB_TMO])) break; if (_sp > XB_SPIN_CAP) { atomicAdd(&(bar)[XB_TMO], 1u); break; } } } } while (0)
; __device__ __forceinline__ void xcd_barrier(const XcdBarrier& b) {
;     ...
;         const unsigned old = xb_add(&bar[XB_XSUB(b.x)], 1u);
;         const unsigned gen = old / nloc;
;         if (old + 1u == (gen + 1u) * nloc) {
;             __builtin_amdgcn_fence(__ATOMIC_RELEASE, "agent");
;             asm volatile("s_waitcnt vmcnt(0)" ::: "memory");
;             const unsigned og = xb_add(&bar[XB_TOP], 1u);
;             const unsigned tg = og / nx;
;             if (og + 1u == (tg + 1u) * nx) xb_add(&bar[XB_TOPGEN], 1u);
;             else XB_SPIN(xb_ld(&bar[XB_TOPGEN]) == tg, bar);
;             __builtin_amdgcn_fence(__ATOMIC_ACQUIRE, "agent");
;             xb_add(&bar[XB_XGEN(b.x)], 1u);
;             asm volatile("s_waitcnt vmcnt(0)" ::: "memory");
;         } else {
;             XB_SPIN(xb_ld(&bar[XB_XGEN(b.x)]) == gen, bar);
.LBB0_327:
	s_or_b64 exec, exec, s[16:17]
	v_cvt_f32_u32_e32 v5, v3
	s_waitcnt vmcnt(0)
	v_readfirstlane_b32 s0, v4
	v_sub_u32_e32 v4, 0, v3
	v_rcp_iflag_f32_e32 v5, v5
	v_add_u32_e32 v6, s0, v0
	v_mul_f32_e32 v5, 0x4f7ffffe, v5
	v_cvt_u32_f32_e32 v5, v5
	v_mul_lo_u32 v0, v4, v5
	v_mul_hi_u32 v0, v5, v0
	v_add_u32_e32 v0, v5, v0
	v_mul_hi_u32 v0, v6, v0
	v_mul_lo_u32 v4, v0, v3
	v_sub_u32_e32 v4, v6, v4
	v_add_u32_e32 v5, 1, v0
	v_cmp_ge_u32_e32 vcc, v4, v3
	s_nop 1
	v_cndmask_b32_e32 v0, v0, v5, vcc
	v_sub_u32_e32 v5, v4, v3
	v_cndmask_b32_e32 v4, v4, v5, vcc
	v_add_u32_e32 v5, 1, v0
	v_cmp_ge_u32_e32 vcc, v4, v3
	v_add_u32_e32 v4, 1, v6
	s_nop 0
	v_cndmask_b32_e32 v0, v0, v5, vcc
	v_mul_lo_u32 v5, v3, v0
	v_add_u32_e32 v3, v5, v3
	v_cmp_ne_u32_e32 vcc, v4, v3
	s_and_saveexec_b64 s[0:1], vcc
	s_xor_b64 s[14:15], exec, s[0:1]
	s_cbranch_execz .LBB0_341
	s_waitcnt lgkmcnt(0)
	v_mov_b32_e32 v2, 0x183500
	buffer_inv sc1
	global_load_dword v2, v2, s[8:9] sc1
	s_add_u32 s20, s8, 0x183500
	s_addc_u32 s21, s9, 0
	s_waitcnt vmcnt(0)
	v_cmp_eq_u32_e32 vcc, v2, v0
	s_and_saveexec_b64 s[16:17], vcc
	s_cbranch_execz .LBB0_340
	s_add_u32 s18, s8, 0x180200
	s_addc_u32 s19, s9, 0
	s_mov_b32 s0, 1
	s_mov_b64 s[22:23], 0
	s_branch .LBB0_331

; __device__ __forceinline__ unsigned xb_ld(unsigned* p)              { return __hip_atomic_load(p, __ATOMIC_RELAXED, __HIP_MEMORY_SCOPE_AGENT); }
; __device__ __forceinline__ unsigned xb_add(unsigned* p, unsigned v) { return __hip_atomic_fetch_add(p, v, __ATOMIC_RELAXED, __HIP_MEMORY_SCOPE_AGENT); }
; #define XB_SPIN(cond, bar) do { unsigned _sp = 0; while (cond) { __builtin_amdgcn_s_sleep(1); \
;     if ((++_sp & 255u) == 0u) { if (xb_ld(&(bar)[XB_TMO])) break; if (_sp > XB_SPIN_CAP) { atomicAdd(&(bar)[XB_TMO], 1u); break; } } } } while (0)
; __device__ __forceinline__ void xcd_barrier(const XcdBarrier& b) {
;     ...
;         const unsigned old = xb_add(&bar[XB_XSUB(b.x)], 1u);
;         const unsigned gen = old / nloc;
;         if (old + 1u == (gen + 1u) * nloc) {
;             __builtin_amdgcn_fence(__ATOMIC_RELEASE, "agent");
;             asm volatile("s_waitcnt vmcnt(0)" ::: "memory");
;             const unsigned og = xb_add(&bar[XB_TOP], 1u);
;             const unsigned tg = og / nx;
;             if (og + 1u == (tg + 1u) * nx) xb_add(&bar[XB_TOPGEN], 1u);
;             else XB_SPIN(xb_ld(&bar[XB_TOPGEN]) == tg, bar);
;             __builtin_amdgcn_fence(__ATOMIC_ACQUIRE, "agent");
;             xb_add(&bar[XB_XGEN(b.x)], 1u);
;             asm volatile("s_waitcnt vmcnt(0)" ::: "memory");
;         } else {
;             XB_SPIN(xb_ld(&bar[XB_XGEN(b.x)]) == gen, bar);
.LBB0_444:
	s_or_b64 exec, exec, s[14:15]
	v_cvt_f32_u32_e32 v5, v3
	s_waitcnt vmcnt(0)
	v_readfirstlane_b32 s0, v4
	v_sub_u32_e32 v4, 0, v3
	v_rcp_iflag_f32_e32 v5, v5
	v_add_u32_e32 v6, s0, v0
	v_mul_f32_e32 v5, 0x4f7ffffe, v5
	v_cvt_u32_f32_e32 v5, v5
	v_mul_lo_u32 v0, v4, v5
	v_mul_hi_u32 v0, v5, v0
	v_add_u32_e32 v0, v5, v0
	v_mul_hi_u32 v0, v6, v0
	v_mul_lo_u32 v4, v0, v3
	v_sub_u32_e32 v4, v6, v4
	v_add_u32_e32 v5, 1, v0
	v_cmp_ge_u32_e32 vcc, v4, v3
	s_nop 1
	v_cndmask_b32_e32 v0, v0, v5, vcc
	v_sub_u32_e32 v5, v4, v3
	v_cndmask_b32_e32 v4, v4, v5, vcc
	v_add_u32_e32 v5, 1, v0
	v_cmp_ge_u32_e32 vcc, v4, v3
	v_add_u32_e32 v4, 1, v6
	s_nop 0
	v_cndmask_b32_e32 v0, v0, v5, vcc
	v_mul_lo_u32 v5, v3, v0
	v_add_u32_e32 v3, v5, v3
	v_cmp_ne_u32_e32 vcc, v4, v3
	s_and_saveexec_b64 s[0:1], vcc
	s_xor_b64 s[12:13], exec, s[0:1]
	s_cbranch_execz .LBB0_458
	s_waitcnt lgkmcnt(0)
	v_mov_b32_e32 v2, 0x183500
	buffer_inv sc1
	global_load_dword v2, v2, s[6:7] sc1
	s_add_u32 s18, s6, 0x183500
	s_addc_u32 s19, s7, 0
	s_waitcnt vmcnt(0)
	v_cmp_eq_u32_e32 vcc, v2, v0
	s_and_saveexec_b64 s[14:15], vcc
	s_cbranch_execz .LBB0_457
	s_add_u32 s16, s6, 0x180200
	s_addc_u32 s17, s7, 0
	s_mov_b32 s0, 1
	s_mov_b64 s[20:21], 0
	s_branch .LBB0_448

; __device__ __forceinline__ unsigned xb_ld(unsigned* p)              { return __hip_atomic_load(p, __ATOMIC_RELAXED, __HIP_MEMORY_SCOPE_AGENT); }
; __device__ __forceinline__ unsigned xb_add(unsigned* p, unsigned v) { return __hip_atomic_fetch_add(p, v, __ATOMIC_RELAXED, __HIP_MEMORY_SCOPE_AGENT); }
; #define XB_SPIN(cond, bar) do { unsigned _sp = 0; while (cond) { __builtin_amdgcn_s_sleep(1); \
;     if ((++_sp & 255u) == 0u) { if (xb_ld(&(bar)[XB_TMO])) break; if (_sp > XB_SPIN_CAP) { atomicAdd(&(bar)[XB_TMO], 1u); break; } } } } while (0)
; __device__ __forceinline__ void xcd_barrier(const XcdBarrier& b) {
;     ...
;         const unsigned old = xb_add(&bar[XB_XSUB(b.x)], 1u);
;         const unsigned gen = old / nloc;
;         if (old + 1u == (gen + 1u) * nloc) {
;             __builtin_amdgcn_fence(__ATOMIC_RELEASE, "agent");
;             asm volatile("s_waitcnt vmcnt(0)" ::: "memory");
;             const unsigned og = xb_add(&bar[XB_TOP], 1u);
;             const unsigned tg = og / nx;
;             if (og + 1u == (tg + 1u) * nx) xb_add(&bar[XB_TOPGEN], 1u);
;             else XB_SPIN(xb_ld(&bar[XB_TOPGEN]) == tg, bar);
;             __builtin_amdgcn_fence(__ATOMIC_ACQUIRE, "agent");
;             xb_add(&bar[XB_XGEN(b.x)], 1u);
;             asm volatile("s_waitcnt vmcnt(0)" ::: "memory");
;         } else {
;             XB_SPIN(xb_ld(&bar[XB_XGEN(b.x)]) == gen, bar);
.LBB0_566:
	s_or_b64 exec, exec, s[12:13]
	v_cvt_f32_u32_e32 v5, v3
	s_waitcnt vmcnt(0)
	v_readfirstlane_b32 s0, v4
	v_sub_u32_e32 v4, 0, v3
	v_rcp_iflag_f32_e32 v5, v5
	v_add_u32_e32 v6, s0, v0
	v_mul_f32_e32 v5, 0x4f7ffffe, v5
	v_cvt_u32_f32_e32 v5, v5
	v_mul_lo_u32 v0, v4, v5
	v_mul_hi_u32 v0, v5, v0
	v_add_u32_e32 v0, v5, v0
	v_mul_hi_u32 v0, v6, v0
	v_mul_lo_u32 v4, v0, v3
	v_sub_u32_e32 v4, v6, v4
	v_add_u32_e32 v5, 1, v0
	v_cmp_ge_u32_e32 vcc, v4, v3
	s_nop 1
	v_cndmask_b32_e32 v0, v0, v5, vcc
	v_sub_u32_e32 v5, v4, v3
	v_cndmask_b32_e32 v4, v4, v5, vcc
	v_add_u32_e32 v5, 1, v0
	v_cmp_ge_u32_e32 vcc, v4, v3
	v_add_u32_e32 v4, 1, v6
	s_nop 0
	v_cndmask_b32_e32 v0, v0, v5, vcc
	v_mul_lo_u32 v5, v3, v0
	v_add_u32_e32 v3, v5, v3
	v_cmp_ne_u32_e32 vcc, v4, v3
	s_and_saveexec_b64 s[0:1], vcc
	s_xor_b64 s[10:11], exec, s[0:1]
	s_cbranch_execz .LBB0_580
	s_waitcnt lgkmcnt(0)
	v_mov_b32_e32 v2, 0x183500
	buffer_inv sc1
	global_load_dword v2, v2, s[6:7] sc1
	s_add_u32 s16, s6, 0x183500
	s_addc_u32 s17, s7, 0
	s_waitcnt vmcnt(0)
	v_cmp_eq_u32_e32 vcc, v2, v0
	s_and_saveexec_b64 s[12:13], vcc
	s_cbranch_execz .LBB0_579
	s_add_u32 s14, s6, 0x180200
	s_addc_u32 s15, s7, 0
	s_mov_b32 s0, 1
	s_mov_b64 s[18:19], 0
	s_branch .LBB0_570
